# PEER chunk start: sub-key staging loop unrolled, its four loads in flight together instead of four serialized round trips
# speedup vs baseline: 1.0106x; 1.0106x over previous
; #define LAS __attribute__((address_space(3)))
; __global__ void __launch_bounds__(NTHR, 2) k_main(Args a) {
;     ...
;             for (int i = tid; i < 2 * 128 * 8; i += NTHR) {
;                 const int pc = i & 7, key = (i >> 3) & 127, hf = (i >> 10) & 1, hl = i >> 11;
;                 *(LAS v4u*)(KHL + ((hl * 2 + hf) * 128 + key) * 72 + pc * 8) = *(const v4u*)((hl ? KL : KH) + (size_t)(hf * 128 + key) * 64 + pc * 8);
;             }
.LBB0_665:
	v_mov_b32_e32 v20, s53
	v_mov_b32_e32 v21, s49
	v_mov_b32_e32 v22, s52
	v_mov_b32_e32 v23, s48
	v_lshlrev_b32_e32 v24, 4, v19
	v_cmp_gt_u32_e32 vcc, s54, v19
	v_lshlrev_b32_e32 v25, 1, v18
	v_and_b32_e32 v82, 0x7f80, v24
	v_cndmask_b32_e32 v21, v20, v21, vcc
	v_cndmask_b32_e32 v20, v22, v23, vcc
	v_lshl_add_u64 v[20:21], v[20:21], 0, v[82:83]
	v_and_b32_e32 v82, 0x70, v25
	v_lshl_add_u64 v[20:21], v[20:21], 0, v[82:83]
	global_load_dwordx4 v[162:165], v[20:21], off
	v_lshrrev_b32_e32 v24, 3, v19
	v_mul_lo_u32 v24, v24, s56
	v_add3_u32 v178, 0, v24, v82
	v_add_u32_e32 v19, 0x200, v19
	v_add_u32_e32 v18, 0x1000, v18
	v_mov_b32_e32 v20, s53
	v_mov_b32_e32 v21, s49
	v_mov_b32_e32 v22, s52
	v_mov_b32_e32 v23, s48
	v_lshlrev_b32_e32 v24, 4, v19
	v_cmp_gt_u32_e32 vcc, s54, v19
	v_lshlrev_b32_e32 v25, 1, v18
	v_and_b32_e32 v82, 0x7f80, v24
	v_cndmask_b32_e32 v21, v20, v21, vcc
	v_cndmask_b32_e32 v20, v22, v23, vcc
	v_lshl_add_u64 v[20:21], v[20:21], 0, v[82:83]
	v_and_b32_e32 v82, 0x70, v25
	v_lshl_add_u64 v[20:21], v[20:21], 0, v[82:83]
	global_load_dwordx4 v[166:169], v[20:21], off
	v_lshrrev_b32_e32 v24, 3, v19
	v_mul_lo_u32 v24, v24, s56
	v_add3_u32 v179, 0, v24, v82
	v_add_u32_e32 v19, 0x200, v19
	v_add_u32_e32 v18, 0x1000, v18
	v_mov_b32_e32 v20, s53
	v_mov_b32_e32 v21, s49
	v_mov_b32_e32 v22, s52
	v_mov_b32_e32 v23, s48
	v_lshlrev_b32_e32 v24, 4, v19
	v_cmp_gt_u32_e32 vcc, s54, v19
	v_lshlrev_b32_e32 v25, 1, v18
	v_and_b32_e32 v82, 0x7f80, v24
	v_cndmask_b32_e32 v21, v20, v21, vcc
	v_cndmask_b32_e32 v20, v22, v23, vcc
	v_lshl_add_u64 v[20:21], v[20:21], 0, v[82:83]
	v_and_b32_e32 v82, 0x70, v25
	v_lshl_add_u64 v[20:21], v[20:21], 0, v[82:83]
	global_load_dwordx4 v[170:173], v[20:21], off
	v_lshrrev_b32_e32 v24, 3, v19
	v_mul_lo_u32 v24, v24, s56
	v_add3_u32 v180, 0, v24, v82
	v_add_u32_e32 v19, 0x200, v19
	v_add_u32_e32 v18, 0x1000, v18
	v_mov_b32_e32 v20, s53
	v_mov_b32_e32 v21, s49
	v_mov_b32_e32 v22, s52
	v_mov_b32_e32 v23, s48
	v_lshlrev_b32_e32 v24, 4, v19
	v_cmp_gt_u32_e32 vcc, s54, v19
	v_lshlrev_b32_e32 v25, 1, v18
	v_and_b32_e32 v82, 0x7f80, v24
	v_cndmask_b32_e32 v21, v20, v21, vcc
	v_cndmask_b32_e32 v20, v22, v23, vcc
	v_lshl_add_u64 v[20:21], v[20:21], 0, v[82:83]
	v_and_b32_e32 v82, 0x70, v25
	v_lshl_add_u64 v[20:21], v[20:21], 0, v[82:83]
	global_load_dwordx4 v[174:177], v[20:21], off
	v_lshrrev_b32_e32 v24, 3, v19
	v_mul_lo_u32 v24, v24, s56
	v_add3_u32 v181, 0, v24, v82
	v_add_u32_e32 v19, 0x200, v19
	v_add_u32_e32 v18, 0x1000, v18
	s_waitcnt vmcnt(0)
	ds_write_b128 v178, v[162:165]
	ds_write_b128 v179, v[166:169]
	ds_write_b128 v180, v[170:173]
	ds_write_b128 v181, v[174:177]
	s_nop 0
	s_nop 0
	s_nop 0
	s_nop 0
	s_nop 0
	s_nop 0
	s_nop 0
	s_nop 0
	s_nop 0
	s_nop 0
	s_nop 0
